# HGRN chunk loop: the mid-chunk full vmcnt drain only has the previous chunk's four output stores behind it - counted wait vmcnt(4), one full drain at the loop entry
# baseline (speedup 1.0000x reference)
.LBB0_202:
	v_add_u32_e32 v9, 0x200, v9
	s_movk_i32 s16, 0x67f
	v_cmp_lt_u32_e32 vcc, s16, v9
	ds_write_b128 v8, v[0:3]
	s_or_b64 s[12:13], vcc, s[12:13]
	v_add_u32_e32 v8, 0x2000, v8
	s_andn2_b64 exec, exec, s[12:13]
	s_cbranch_execnz .LBB0_202
	s_or_b64 exec, exec, s[12:13]
	s_waitcnt vmcnt(0)
	v_sub_f32_e32 v4, v6, v4
	v_sub_f32_e32 v5, v7, v5
	v_mul_f32_e32 v4, 0x3fb8aa3b, v4
	v_mul_f32_e32 v5, 0x3fb8aa3b, v5
	v_exp_f32_e32 v4, v4
	v_exp_f32_e32 v5, v5
	s_and_b32 s29, s15, 0xfffff800
	v_readfirstlane_b32 s36, v183
	s_ashr_i32 s30, s29, 31
	v_pk_add_f32 v[4:5], v[4:5], 1.0 op_sel_hi:[1,0]
	s_mul_i32 s34, s29, 0xc000
	v_div_scale_f32 v6, s[12:13], v5, v5, 1.0
	v_rcp_f32_e32 v7, v6
	s_lshr_b32 s35, s36, 6
	s_mul_hi_i32 s31, s29, 0xc000
	s_mul_i32 s37, s35, 0x60000
	v_fma_f32 v8, -v6, v7, 1.0
	v_fmac_f32_e32 v7, v8, v7
	v_div_scale_f32 v8, vcc, 1.0, v5, 1.0
	v_mul_f32_e32 v9, v8, v7
	v_fma_f32 v10, -v6, v9, v8
	v_fmac_f32_e32 v9, v10, v7
	v_fma_f32 v6, -v6, v9, v8
	v_div_scale_f32 v8, s[12:13], v4, v4, 1.0
	v_rcp_f32_e32 v10, v8
	v_div_fmas_f32 v6, v6, v7, v9
	v_div_fixup_f32 v89, v6, v5, 1.0
	s_add_u32 s12, s74, s34
	v_fma_f32 v5, -v8, v10, 1.0
	v_fmac_f32_e32 v10, v5, v10
	v_div_scale_f32 v5, vcc, 1.0, v4, 1.0
	v_mul_f32_e32 v6, v5, v10
	s_addc_u32 s13, s75, s31
	s_lshl_b32 s15, s35, 3
	v_fma_f32 v7, -v8, v6, v5
	s_mul_hi_u32 s15, s15, 0xc000
	s_add_u32 s12, s12, s37
	v_fmac_f32_e32 v6, v7, v10
	s_addc_u32 s13, s13, s15
	s_lshl_b32 s14, s14, 1
	v_fma_f32 v5, -v8, v6, v5
	s_add_u32 s12, s12, s14
	v_div_fmas_f32 v5, v5, v10, v6
	s_addc_u32 s13, s13, 0
	v_lshlrev_b32_e32 v74, 1, v72
	v_div_fixup_f32 v88, v5, v4, 1.0
	v_lshl_add_u64 v[4:5], s[12:13], 0, v[74:75]
	s_movk_i32 s14, 0x2000
	v_add_co_u32_e32 v6, vcc, s14, v4
	s_mov_b32 s14, 0xe000
	s_nop 0
	v_addc_co_u32_e32 v7, vcc, 0, v5, vcc
	v_add_co_u32_e32 v8, vcc, s14, v4
	s_mov_b32 s14, 0xc000
	s_nop 0
	v_addc_co_u32_e32 v9, vcc, 0, v5, vcc
	v_add_co_u32_e32 v10, vcc, s14, v4
	s_mov_b32 s14, 0x1a000
	s_nop 0
	v_addc_co_u32_e32 v11, vcc, 0, v5, vcc
	v_add_co_u32_e32 v12, vcc, s14, v4
	s_mov_b32 s14, 0x18000
	s_nop 0
	v_addc_co_u32_e32 v13, vcc, 0, v5, vcc
	v_add_co_u32_e32 v14, vcc, s14, v4
	s_mov_b32 s14, 0x26000
	s_nop 0
	v_addc_co_u32_e32 v15, vcc, 0, v5, vcc
	v_add_co_u32_e32 v16, vcc, s14, v4
	s_mov_b32 s14, 0x24000
	s_nop 0
	v_addc_co_u32_e32 v17, vcc, 0, v5, vcc
	v_add_co_u32_e32 v18, vcc, s14, v4
	s_mov_b32 s14, 0x32000
	s_nop 0
	v_addc_co_u32_e32 v19, vcc, 0, v5, vcc
	global_load_dword v152, v[6:7], off offset:-4096 nt
	global_load_dword v153, v[6:7], off nt
	global_load_dword v154, v[8:9], off offset:-4096 nt
	global_load_dword v155, v[8:9], off nt
	global_load_dword v156, v[12:13], off offset:-4096 nt
	global_load_dword v161, v[12:13], off nt
	global_load_dword v162, v[16:17], off offset:-4096 nt
	global_load_dword v163, v[16:17], off nt
	v_add_co_u32_e32 v6, vcc, s14, v4
	s_mov_b32 s14, 0x30000
	s_nop 0
	v_addc_co_u32_e32 v7, vcc, 0, v5, vcc
	v_add_co_u32_e32 v8, vcc, s14, v4
	s_mov_b32 s14, 0x3e000
	s_nop 0
	v_addc_co_u32_e32 v9, vcc, 0, v5, vcc
	v_add_co_u32_e32 v12, vcc, s14, v4
	s_mov_b32 s14, 0x3c000
	s_nop 0
	v_addc_co_u32_e32 v13, vcc, 0, v5, vcc
	v_add_co_u32_e32 v16, vcc, s14, v4
	s_mov_b32 s14, 0x4a000
	s_nop 0
	v_addc_co_u32_e32 v17, vcc, 0, v5, vcc
	v_add_co_u32_e32 v20, vcc, s14, v4
	s_mov_b32 s14, 0x48000
	s_nop 0
	v_addc_co_u32_e32 v21, vcc, 0, v5, vcc
	v_add_co_u32_e32 v22, vcc, s14, v4
	s_mov_b32 s14, 0x56000
	s_nop 0
	v_addc_co_u32_e32 v23, vcc, 0, v5, vcc
	v_add_co_u32_e32 v24, vcc, s14, v4
	s_mov_b32 s14, 0x54000
	s_nop 0
	v_addc_co_u32_e32 v25, vcc, 0, v5, vcc
	v_add_co_u32_e32 v4, vcc, s14, v4
	s_bfe_u32 s40, s36, 0x20006
	s_nop 0
	v_addc_co_u32_e32 v5, vcc, 0, v5, vcc
	global_load_dword v157, v74, s[12:13] nt
	global_load_dword v160, v[10:11], off nt
	global_load_dword v164, v[14:15], off nt
	global_load_dword v165, v[18:19], off nt
	global_load_dword v180, v[8:9], off nt
	global_load_dword v184, v[16:17], off nt
	global_load_dword v188, v[22:23], off nt
	global_load_dword v191, v[4:5], off nt
	global_load_dword v179, v[6:7], off offset:-4096 nt
	global_load_dword v181, v[6:7], off nt
	global_load_dword v185, v[12:13], off offset:-4096 nt
	global_load_dword v186, v[12:13], off nt
	global_load_dword v187, v[20:21], off offset:-4096 nt
	global_load_dword v189, v[20:21], off nt
	global_load_dword v190, v[24:25], off offset:-4096 nt
	global_load_dword v192, v[24:25], off nt
	s_and_b32 s39, s35, 0x3fffffc
	s_lshl_b32 s76, s35, 9
	s_cmp_lt_u32 s36, 64
	s_cselect_b64 s[84:85], -1, 0
	s_and_b32 s12, s36, 0xffffff00
	s_add_i32 s12, s3, s12
	s_lshl_b32 s13, s40, 6
	s_add_i32 s12, s12, s13
	s_lshl_b32 s77, s35, 5
	s_and_b32 s41, s36, 0xffffffc0
	s_lshl_b32 s56, s39, 6
	s_cmpk_gt_u32 s36, 0x7f
	v_lshl_add_u32 v158, v169, 2, s12
	s_cselect_b64 s[12:13], -1, 0
	s_cmpk_gt_u32 s36, 0xbf
	s_cselect_b64 s[14:15], -1, 0
	s_cmpk_gt_u32 s36, 0xff
	s_cselect_b64 s[16:17], -1, 0
	s_cmpk_gt_u32 s36, 0x13f
	s_cselect_b64 s[18:19], -1, 0
	s_cmpk_gt_u32 s36, 0x17f
	s_cselect_b64 s[20:21], -1, 0
	s_cmpk_gt_u32 s36, 0x1bf
	s_cselect_b64 s[22:23], -1, 0
	s_cmpk_gt_u32 s36, 0x1ff
	s_cselect_b64 s[24:25], -1, 0
	s_or_b32 s43, s39, 1
	s_or_b32 s44, s39, 2
	s_or_b32 s45, s35, 3
	s_cmp_eq_u32 s40, 0
	s_cselect_b64 s[26:27], -1, 0
	s_cmp_lg_u32 s40, 0
	s_cselect_b64 s[86:87], -1, 0
	s_cmp_eq_u32 s40, 1
	s_cselect_b64 s[54:55], -1, 0
	s_cmp_gt_u32 s40, 1
	s_cselect_b64 s[72:73], -1, 0
	s_cmp_eq_u32 s40, 2
	s_cselect_b64 s[78:79], -1, 0
	s_cmp_eq_u32 s40, 3
	v_lshl_or_b32 v5, s39, 4, v169
	v_and_b32_e32 v92, 48, v182
	v_add_u32_e32 v92, s56, v92
	v_add_u32_e32 v92, 0x1d000, v92
	s_cselect_b64 s[88:89], -1, 0
	v_mul_lo_u32 v13, v5, s90
	v_lshl_or_b32 v5, s43, 4, v169
	s_lshl_b32 s56, s43, 6
	v_mul_lo_u32 v14, v5, s90
	v_lshl_or_b32 v5, s44, 4, v169
	s_lshl_b32 s56, s44, 6
	v_lshl_or_b32 v4, s40, 4, v169
	v_mul_lo_u32 v15, v5, s90
	v_lshl_or_b32 v5, s45, 4, v169
	s_lshl_b32 s56, s45, 6
	s_and_b32 s28, s28, 15
	v_mul_u32_u24_e32 v8, 0x110, v4
	v_lshl_add_u32 v159, v4, 2, s3
	v_mul_lo_u32 v16, v5, s90
	s_lshl_b32 s56, s28, 8
	v_or_b32_e32 v4, s29, v4
	v_mov_b32_e32 v5, s30
	s_lshr_b32 s28, s36, 1
	s_lshl_b32 s38, s45, 5
	v_lshlrev_b64 v[4:5], 12, v[4:5]
	s_and_b32 s28, s28, 0x7fffff80
	s_mov_b32 s29, s57
	v_lshl_add_u64 v[6:7], v[4:5], 0, s[28:29]
	s_mul_hi_u32 s29, s35, 0x60000
	s_add_u32 s36, s37, s34
	s_addc_u32 s37, s29, s31
	v_lshl_or_b32 v9, s39, 5, v132
	s_mov_b32 s39, s57
	s_add_u32 s28, s34, s28
	s_mul_i32 s40, s40, 0x60000
	v_lshl_add_u64 v[4:5], v[4:5], 0, s[38:39]
	s_addc_u32 s29, s31, 0
	v_add_lshl_u32 v74, v150, s40, 1
	v_lshl_add_u64 v[104:105], v[82:83], 0, v[4:5]
	v_lshl_add_u64 v[4:5], s[28:29], 0, v[74:75]
	s_add_u32 s28, s34, s38
	s_addc_u32 s29, s31, 0
	s_mul_i32 s42, s35, 0x880
	v_lshl_or_b32 v10, s43, 5, v132
	v_lshl_or_b32 v11, s44, 5, v132
	v_or_b32_e32 v12, s38, v132
	v_lshl_add_u64 v[106:107], v[84:85], 0, v[4:5]
	v_lshl_add_u64 v[4:5], s[28:29], 0, v[74:75]
	v_mov_b32_e32 v28, 0
	v_pk_add_f32 v[90:91], v[88:89], 1.0 op_sel_hi:[1,0] neg_lo:[1,0] neg_hi:[1,0]
	v_lshl_add_u64 v[100:101], v[80:81], 0, v[6:7]
	v_lshl_add_u64 v[102:103], v[78:79], 0, s[36:37]
	v_lshl_add_u64 v[108:109], v[86:87], 0, v[4:5]
	s_mov_b32 s96, 32
	v_add_u32_e32 v74, s42, v137
	v_add_u32_e32 v166, v139, v8
	v_add_u32_e32 v167, v140, v13
	v_add_u32_e32 v168, v140, v14
	v_add_u32_e32 v171, v140, v15
	v_add_u32_e32 v172, v140, v16
	v_add_u32_e32 v173, s41, v141
	v_add_u32_e32 v174, s77, v143
	v_add_u32_e32 v175, v144, v9
	v_add_u32_e32 v176, v144, v10
	v_add_u32_e32 v177, v144, v11
	v_add_u32_e32 v178, v144, v12
	v_mov_b32_e32 v29, v28
	v_mov_b32_e32 v30, v28
	v_mov_b32_e32 v31, v28
	v_mov_b32_e32 v32, v28
	v_mov_b32_e32 v33, v28
	v_mov_b32_e32 v34, v28
	v_mov_b32_e32 v35, v28
	v_mov_b32_e32 v24, v28
	v_mov_b32_e32 v25, v28
	v_mov_b32_e32 v26, v28
	v_mov_b32_e32 v27, v28
	v_mov_b32_e32 v20, v28
	v_mov_b32_e32 v21, v28
	v_mov_b32_e32 v22, v28
	v_mov_b32_e32 v23, v28
	v_mov_b32_e32 v16, v28
	v_mov_b32_e32 v17, v28
	v_mov_b32_e32 v18, v28
	v_mov_b32_e32 v19, v28
	v_mov_b32_e32 v12, v28
	v_mov_b32_e32 v13, v28
	v_mov_b32_e32 v14, v28
	v_mov_b32_e32 v15, v28
	v_mov_b32_e32 v8, v28
	v_mov_b32_e32 v9, v28
	v_mov_b32_e32 v10, v28
	v_mov_b32_e32 v11, v28
	v_mov_b32_e32 v4, v28
	v_mov_b32_e32 v5, v28
	v_mov_b32_e32 v6, v28
	v_mov_b32_e32 v7, v28
	s_waitcnt vmcnt(0)
	s_branch .LBB0_205

.LBB0_205:
	s_waitcnt vmcnt(23)
	v_lshlrev_b32_e32 v46, 16, v152
	v_mul_f32_e64 v36, |v46|, s91
	v_exp_f32_e32 v38, v36
	v_and_b32_e32 v47, 0xffff0000, v152
	s_waitcnt vmcnt(21)
	v_lshlrev_b32_e32 v48, 16, v154
	v_and_b32_e32 v49, 0xffff0000, v154
	v_add_f32_e32 v36, 1.0, v38
	v_rcp_f32_e32 v40, v36
	v_mul_f32_e64 v36, |v47|, s91
	v_exp_f32_e32 v43, v36
	v_cmp_le_f32_e64 s[28:29], 0, v46
	v_cmp_le_f32_e64 s[34:35], 0, v47
	v_cmp_le_f32_e64 s[30:31], 0, v48
	v_add_f32_e32 v36, 1.0, v43
	v_rcp_f32_e32 v45, v36
	v_mul_f32_e64 v36, |v48|, s91
	v_exp_f32_e32 v42, v36
	v_cmp_le_f32_e32 vcc, 0, v49
	s_waitcnt vmcnt(19)
	v_lshlrev_b32_e32 v50, 16, v156
	v_and_b32_e32 v51, 0xffff0000, v156
	v_add_f32_e32 v36, 1.0, v42
	v_rcp_f32_e32 v44, v36
	v_mul_f32_e64 v36, |v49|, s91
	v_exp_f32_e32 v39, v36
	s_waitcnt vmcnt(17)
	v_lshlrev_b32_e32 v68, 16, v162
	v_pk_mul_f32 v[42:43], v[42:43], v[44:45]
	v_and_b32_e32 v69, 0xffff0000, v162
	v_add_f32_e32 v36, 1.0, v39
	v_rcp_f32_e32 v41, v36
	v_cndmask_b32_e64 v47, v43, v45, s[34:35]
	s_waitcnt vmcnt(7)
	v_lshlrev_b32_e32 v112, 16, v179
	v_and_b32_e32 v113, 0xffff0000, v179
	v_pk_mul_f32 v[38:39], v[38:39], v[40:41]
	v_cmp_le_f32_e64 s[36:37], 0, v112
	v_cndmask_b32_e64 v46, v40, v38, s[28:29]
	v_mul_f32_e32 v195, v90, v46
	v_cndmask_b32_e64 v46, v45, v43, s[34:35]
	v_mul_f32_e32 v193, v91, v46
	v_cndmask_b32_e64 v46, v42, v44, s[30:31]
	v_cndmask_b32_e64 v42, v44, v42, s[30:31]
	v_mul_f32_e32 v194, v90, v42
	v_cndmask_b32_e32 v43, v39, v41, vcc
	v_cndmask_b32_e64 v42, v38, v40, s[28:29]
	v_pk_fma_f32 v[56:57], v[90:91], v[46:47], v[88:89]
	v_cndmask_b32_e32 v38, v41, v39, vcc
	v_pk_fma_f32 v[58:59], v[90:91], v[42:43], v[88:89]
	v_cmp_le_f32_e32 vcc, 0, v50
	v_pk_mul_f32 v[54:55], v[56:57], v[58:59]
	v_mul_f32_e32 v56, v91, v38
	v_mul_f32_e64 v38, |v50|, s91
	v_exp_f32_e32 v38, v38
	v_cmp_le_f32_e64 s[28:29], 0, v51
	v_cmp_le_f32_e64 s[30:31], 0, v68
	v_cmp_le_f32_e64 s[34:35], 0, v69
	v_add_f32_e32 v39, 1.0, v38
	v_rcp_f32_e32 v52, v39
	v_mul_f32_e64 v39, |v51|, s91
	v_exp_f32_e32 v39, v39
	v_cmp_le_f32_e64 s[38:39], 0, v113
	s_waitcnt vmcnt(5)
	v_lshlrev_b32_e32 v118, 16, v185
	v_and_b32_e32 v119, 0xffff0000, v185
	v_add_f32_e32 v40, 1.0, v39
	v_rcp_f32_e32 v53, v40
	v_cmp_le_f32_e64 s[40:41], 0, v118
	v_cmp_le_f32_e64 s[42:43], 0, v119
	s_waitcnt vmcnt(3)
	v_lshlrev_b32_e32 v124, 16, v187
	v_pk_mul_f32 v[60:61], v[38:39], v[52:53]
	v_and_b32_e32 v125, 0xffff0000, v187
	v_cndmask_b32_e64 v39, v61, v53, s[28:29]
	v_cndmask_b32_e32 v38, v60, v52, vcc
	v_pk_fma_f32 v[38:39], v[90:91], v[38:39], v[88:89]
	v_cmp_le_f32_e64 s[44:45], 0, v124
	v_pk_mul_f32 v[62:63], v[54:55], v[38:39]
	v_mul_f32_e64 v38, |v68|, s91
	v_exp_f32_e32 v38, v38
	v_cmp_le_f32_e64 s[46:47], 0, v125
	s_waitcnt vmcnt(1)
	v_lshlrev_b32_e32 v37, 16, v190
	v_and_b32_e32 v36, 0xffff0000, v190
	v_add_f32_e32 v39, 1.0, v38
	v_rcp_f32_e32 v64, v39
	v_mul_f32_e64 v39, |v69|, s91
	v_exp_f32_e32 v39, v39
	v_cmp_le_f32_e64 s[48:49], 0, v37
	v_cmp_le_f32_e64 s[50:51], 0, v36
	v_cndmask_b32_e64 v53, v53, v61, s[28:29]
	v_add_f32_e32 v40, 1.0, v39
	v_rcp_f32_e32 v65, v40
	v_cndmask_b32_e32 v52, v52, v60, vcc
	v_pk_mul_f32 v[52:53], v[90:91], v[52:53]
	s_andn2_b64 vcc, exec, s[84:85]
	v_pk_mul_f32 v[66:67], v[38:39], v[64:65]
	s_nop 0
	v_cndmask_b32_e64 v39, v67, v65, s[34:35]
	v_cndmask_b32_e64 v38, v66, v64, s[30:31]
	v_pk_fma_f32 v[38:39], v[90:91], v[38:39], v[88:89]
	s_nop 0
	v_pk_mul_f32 v[68:69], v[62:63], v[38:39]
	v_mul_f32_e64 v38, |v112|, s91
	v_exp_f32_e32 v38, v38
	s_nop 0
	v_add_f32_e32 v39, 1.0, v38
	v_rcp_f32_e32 v70, v39
	v_mul_f32_e64 v39, |v113|, s91
	v_exp_f32_e32 v39, v39
	s_nop 0
	v_add_f32_e32 v40, 1.0, v39
	v_rcp_f32_e32 v71, v40
	s_nop 0
	v_pk_mul_f32 v[110:111], v[38:39], v[70:71]
	s_nop 0
	v_cndmask_b32_e64 v39, v111, v71, s[38:39]
	v_cndmask_b32_e64 v38, v110, v70, s[36:37]
	v_pk_fma_f32 v[38:39], v[90:91], v[38:39], v[88:89]
	s_nop 0
	v_pk_mul_f32 v[112:113], v[68:69], v[38:39]
	v_mul_f32_e64 v38, |v118|, s91
	v_exp_f32_e32 v38, v38
	s_nop 0
	v_add_f32_e32 v39, 1.0, v38
	v_rcp_f32_e32 v114, v39
	v_mul_f32_e64 v39, |v119|, s91
	v_exp_f32_e32 v39, v39
	s_nop 0
	v_add_f32_e32 v40, 1.0, v39
	v_rcp_f32_e32 v115, v40
	s_nop 0
	v_pk_mul_f32 v[116:117], v[38:39], v[114:115]
	s_nop 0
	v_cndmask_b32_e64 v39, v117, v115, s[42:43]
	v_cndmask_b32_e64 v38, v116, v114, s[40:41]
	v_pk_fma_f32 v[38:39], v[90:91], v[38:39], v[88:89]
	s_nop 0
	v_pk_mul_f32 v[118:119], v[112:113], v[38:39]
	v_mul_f32_e64 v38, |v124|, s91
	v_exp_f32_e32 v38, v38
	s_nop 0
	v_add_f32_e32 v39, 1.0, v38
	v_rcp_f32_e32 v120, v39
	v_mul_f32_e64 v39, |v125|, s91
	v_exp_f32_e32 v39, v39
	s_nop 0
	v_add_f32_e32 v40, 1.0, v39
	v_rcp_f32_e32 v121, v40
	s_nop 0
	v_pk_mul_f32 v[122:123], v[38:39], v[120:121]
	s_nop 0
	v_cndmask_b32_e64 v39, v123, v121, s[46:47]
	v_cndmask_b32_e64 v38, v122, v120, s[44:45]
	v_pk_fma_f32 v[38:39], v[90:91], v[38:39], v[88:89]
	s_nop 0
	v_pk_mul_f32 v[124:125], v[118:119], v[38:39]
	v_mul_f32_e64 v38, |v37|, s91
	v_exp_f32_e32 v38, v38
	s_nop 0
	v_add_f32_e32 v39, 1.0, v38
	v_rcp_f32_e32 v126, v39
	v_mul_f32_e64 v39, |v36|, s91
	v_exp_f32_e32 v39, v39
	s_nop 0
	v_add_f32_e32 v40, 1.0, v39
	v_rcp_f32_e32 v127, v40
	s_nop 0
	v_pk_mul_f32 v[128:129], v[38:39], v[126:127]
	s_nop 0
	v_cndmask_b32_e64 v37, v129, v127, s[50:51]
	v_cndmask_b32_e64 v36, v128, v126, s[48:49]
	v_pk_fma_f32 v[36:37], v[90:91], v[36:37], v[88:89]
	s_nop 0
	v_pk_mul_f32 v[130:131], v[124:125], v[36:37]
	v_add_u32_e32 v36, s76, v136
	ds_write_b64 v36, v[130:131]
	s_waitcnt lgkmcnt(0)
	s_barrier
	ds_read2st64_b64 v[36:39], v136 offset1:1
	s_waitcnt lgkmcnt(0)
	v_cndmask_b32_e64 v40, v36, 1.0, s[84:85]
	v_cndmask_b32_e64 v42, 1.0, v38, s[12:13]
	v_cndmask_b32_e64 v41, v37, 1.0, s[84:85]
	v_mul_f32_e32 v44, v40, v42
	v_cndmask_b32_e64 v40, 1.0, v39, s[12:13]
	v_mul_f32_e32 v45, v41, v40
	ds_read2st64_b64 v[40:43], v136 offset0:2 offset1:3
	s_waitcnt lgkmcnt(0)
	v_cndmask_b32_e64 v46, 1.0, v40, s[14:15]
	v_mul_f32_e32 v44, v44, v46
	v_cndmask_b32_e64 v46, 1.0, v41, s[14:15]
	v_mul_f32_e32 v45, v45, v46
	v_cndmask_b32_e64 v46, 1.0, v42, s[16:17]
	v_mul_f32_e32 v48, v44, v46
	v_cndmask_b32_e64 v44, 1.0, v43, s[16:17]
	v_mul_f32_e32 v49, v45, v44
	ds_read2st64_b64 v[44:47], v136 offset0:4 offset1:5
	s_waitcnt lgkmcnt(0)
	v_cndmask_b32_e64 v50, 1.0, v44, s[18:19]
	v_mul_f32_e32 v48, v48, v50
	v_cndmask_b32_e64 v50, 1.0, v45, s[18:19]
	v_mul_f32_e32 v49, v49, v50
	v_cndmask_b32_e64 v50, 1.0, v46, s[20:21]
	v_mul_f32_e32 v59, v48, v50
	v_cndmask_b32_e64 v48, 1.0, v47, s[20:21]
	v_mul_f32_e32 v196, v49, v48
	ds_read2st64_b64 v[48:51], v136 offset0:6 offset1:7
	s_waitcnt lgkmcnt(0)
	v_cndmask_b32_e64 v197, 1.0, v48, s[22:23]
	v_mul_f32_e32 v59, v59, v197
	v_cndmask_b32_e64 v197, 1.0, v49, s[22:23]
	v_mul_f32_e32 v196, v196, v197
	v_cndmask_b32_e64 v197, 1.0, v50, s[24:25]
	v_mul_f32_e32 v59, v59, v197
	v_cndmask_b32_e64 v197, 1.0, v51, s[24:25]
	v_mul_f32_e32 v58, v58, v59
	v_mul_f32_e32 v196, v196, v197
	v_rcp_f32_e32 v197, v58
	v_mul_f32_e32 v57, v57, v196
	v_mul_f32_e32 v54, v54, v59
	v_mul_f32_e32 v55, v55, v196
	v_mul_f32_e32 v195, v195, v197
	v_rcp_f32_e32 v197, v57
	v_mul_f32_e32 v61, v68, v59
	v_mul_f32_e32 v193, v193, v197
	v_lshlrev_b32_e32 v197, 16, v157
	v_mul_f32_e32 v58, v58, v197
	v_and_b32_e32 v197, 0xffff0000, v157
	v_mul_f32_e32 v57, v57, v197
	v_cvt_pk_bf16_f32 v57, v58, v57
	v_cvt_pk_bf16_f32 v58, v195, v193
	v_rcp_f32_e32 v193, v54
	s_nop 0
	v_mul_f32_e32 v193, v194, v193
	v_rcp_f32_e32 v194, v55
	s_nop 0
	v_mul_f32_e32 v56, v56, v194
	v_lshlrev_b32_e32 v194, 16, v160
	v_mul_f32_e32 v54, v54, v194
	v_and_b32_e32 v194, 0xffff0000, v160
	v_mul_f32_e32 v55, v55, v194
	v_cvt_pk_bf16_f32 v54, v54, v55
	ds_write2_b32 v74, v57, v54 offset1:68
	v_cvt_pk_bf16_f32 v54, v193, v56
	v_add_u32_e32 v56, 0x4400, v74
	ds_write2_b32 v56, v58, v54 offset1:68
	v_mul_f32_e32 v58, v62, v59
	v_mul_f32_e32 v62, v63, v196
	v_rcp_f32_e32 v54, v58
	v_rcp_f32_e32 v55, v62
	v_add_u32_e32 v57, 0xcc00, v74
	ds_write2_b32 v57, v153, v155 offset1:68
	v_pk_mul_f32 v[52:53], v[52:53], v[54:55]
	v_and_b32_e32 v55, 0xffff0000, v164
	v_mul_f32_e32 v55, v62, v55
	v_mul_f32_e32 v62, v69, v196
	v_lshlrev_b32_e32 v54, 16, v164
	v_cvt_pk_bf16_f32 v60, v52, v53
	v_rcp_f32_e32 v52, v61
	v_rcp_f32_e32 v53, v62
	v_mul_f32_e32 v54, v58, v54
	v_cvt_pk_bf16_f32 v58, v54, v55
	v_cndmask_b32_e64 v55, v65, v67, s[34:35]
	v_cndmask_b32_e64 v54, v64, v66, s[30:31]
	v_pk_mul_f32 v[54:55], v[90:91], v[54:55]
	s_nop 0
	v_pk_mul_f32 v[52:53], v[54:55], v[52:53]
	v_lshlrev_b32_e32 v54, 16, v165
	v_and_b32_e32 v55, 0xffff0000, v165
	v_mul_f32_e32 v54, v61, v54
	v_mul_f32_e32 v55, v62, v55
	v_cvt_pk_bf16_f32 v54, v54, v55
	v_cvt_pk_bf16_f32 v52, v52, v53
	ds_write2_b32 v74, v58, v54 offset0:136 offset1:204
	ds_write2_b32 v56, v60, v52 offset0:136 offset1:204
	ds_write2_b32 v57, v161, v163 offset0:136 offset1:204
	v_mul_f32_e32 v56, v112, v59
	v_mul_f32_e32 v57, v113, v196
	v_rcp_f32_e32 v52, v56
	v_rcp_f32_e32 v53, v57
	v_cndmask_b32_e64 v55, v71, v111, s[38:39]
	v_cndmask_b32_e64 v54, v70, v110, s[36:37]
	v_pk_mul_f32 v[54:55], v[90:91], v[54:55]
	v_mul_f32_e32 v58, v118, v59
	v_pk_mul_f32 v[52:53], v[54:55], v[52:53]
	v_and_b32_e32 v55, 0xffff0000, v180
	v_mul_f32_e32 v60, v119, v196
	v_lshlrev_b32_e32 v54, 16, v180
	v_mul_f32_e32 v55, v57, v55
	v_cvt_pk_bf16_f32 v57, v52, v53
	v_rcp_f32_e32 v52, v58
	v_rcp_f32_e32 v53, v60
	v_mul_f32_e32 v54, v56, v54
	v_cvt_pk_bf16_f32 v56, v54, v55
	v_cndmask_b32_e64 v55, v115, v117, s[42:43]
	v_cndmask_b32_e64 v54, v114, v116, s[40:41]
	v_pk_mul_f32 v[54:55], v[90:91], v[54:55]
	v_mul_f32_e32 v61, v125, v196
	v_pk_mul_f32 v[52:53], v[54:55], v[52:53]
	v_lshlrev_b32_e32 v54, 16, v184
	v_and_b32_e32 v55, 0xffff0000, v184
	v_mul_f32_e32 v54, v58, v54
	v_mul_f32_e32 v55, v60, v55
	v_cvt_pk_bf16_f32 v54, v54, v55
	v_add_u32_e32 v58, 0x400, v74
	ds_write2_b32 v58, v56, v54 offset0:16 offset1:84
	v_cvt_pk_bf16_f32 v52, v52, v53
	v_add_u32_e32 v56, 0x4800, v74
	v_mul_f32_e32 v60, v124, v59
	ds_write2_b32 v56, v57, v52 offset0:16 offset1:84
	v_rcp_f32_e32 v52, v60
	v_rcp_f32_e32 v53, v61
	v_cndmask_b32_e64 v55, v121, v123, s[46:47]
	v_cndmask_b32_e64 v54, v120, v122, s[44:45]
	v_pk_mul_f32 v[54:55], v[90:91], v[54:55]
	v_mul_f32_e32 v59, v130, v59
	v_pk_mul_f32 v[52:53], v[54:55], v[52:53]
	v_and_b32_e32 v55, 0xffff0000, v188
	v_mul_f32_e32 v62, v131, v196
	v_lshlrev_b32_e32 v54, 16, v188
	v_mul_f32_e32 v55, v61, v55
	v_cvt_pk_bf16_f32 v61, v52, v53
	v_rcp_f32_e32 v52, v59
	v_rcp_f32_e32 v53, v62
	v_mul_f32_e32 v54, v60, v54
	v_cvt_pk_bf16_f32 v60, v54, v55
	v_cndmask_b32_e64 v55, v127, v129, s[50:51]
	v_cndmask_b32_e64 v54, v126, v128, s[48:49]
	v_pk_mul_f32 v[54:55], v[90:91], v[54:55]
	v_add_u32_e32 v57, 0xd000, v74
	v_pk_mul_f32 v[52:53], v[54:55], v[52:53]
	v_lshlrev_b32_e32 v54, 16, v191
	v_and_b32_e32 v55, 0xffff0000, v191
	v_mul_f32_e32 v54, v59, v54
	v_mul_f32_e32 v55, v62, v55
	v_cvt_pk_bf16_f32 v54, v54, v55
	v_cvt_pk_bf16_f32 v52, v52, v53
	ds_write2_b32 v57, v181, v186 offset0:16 offset1:84
	ds_write2_b32 v58, v60, v54 offset0:152 offset1:220
	ds_write2_b32 v56, v61, v52 offset0:152 offset1:220
	s_waitcnt vmcnt(4)
	ds_write2_b32 v57, v189, v192 offset0:152 offset1:220
	s_cbranch_vccnz .LBB0_207
	v_pk_mul_f32 v[36:37], v[36:37], v[38:39]
	s_nop 0
	v_pk_mul_f32 v[36:37], v[36:37], v[40:41]
	s_nop 0
	v_pk_mul_f32 v[36:37], v[36:37], v[42:43]
	s_nop 0
	v_pk_mul_f32 v[36:37], v[36:37], v[44:45]
	s_nop 0
	v_pk_mul_f32 v[36:37], v[36:37], v[46:47]
	s_nop 0
	v_pk_mul_f32 v[36:37], v[36:37], v[48:49]
	s_nop 0
	v_pk_mul_f32 v[36:37], v[36:37], v[50:51]
	ds_write_b64 v138, v[36:37]
